# SO1+cvtpk + s_setprio 3 on the scan's side-work waves (4-7) while they compete with the chunk-chain waves
# baseline (speedup 1.0000x reference)
.LBB0_436:
	s_waitcnt vmcnt(0)
	s_or_b64 s[10:11], s[82:83], s[56:57]
	s_and_b64 vcc, exec, s[10:11]
	s_waitcnt lgkmcnt(0)
	s_barrier
	s_cbranch_vccnz .LBB0_438
	s_setprio 3
	v_mov_b32_e32 v98, v1
	v_readlane_b32 s10, v255, 25
	v_lshlrev_b32_e32 v34, 7, v98
	v_ashrrev_i32_e32 v36, 1, v98
	v_and_b32_e32 v106, 0x780, v34
	v_readlane_b32 s11, v255, 26
	v_and_b32_e32 v36, -8, v36
	v_ashrrev_i32_e32 v37, 31, v36
	v_lshl_add_u64 v[34:35], s[10:11], 0, v[106:107]
	v_lshl_add_u64 v[34:35], v[36:37], 1, v[34:35]
	s_mov_b32 s31, s41
	v_lshl_add_u64 v[34:35], v[34:35], 0, s[30:31]
	s_movk_i32 s10, 0x1000
	v_add_co_u32_e32 v36, vcc, s10, v34
	s_mov_b32 s10, 0x40000
	s_nop 0
	v_addc_co_u32_e32 v37, vcc, 0, v35, vcc
	v_add_co_u32_e32 v42, vcc, s10, v34
	s_add_i32 s14, 0, 0x22000
	s_lshl_b32 s15, s49, 6
	v_addc_co_u32_e32 v43, vcc, 0, v35, vcc
	s_mov_b32 s10, 0x41000
	s_sub_i32 s16, s63, s73
	v_add_co_u32_e32 v86, vcc, s10, v34
	s_and_b64 s[10:11], s[8:9], exec
	s_cselect_b32 s16, s15, s16
	s_add_i32 s17, s15, s0
	s_sub_i32 s18, s71, s17
	s_and_b64 s[10:11], s[8:9], exec
	v_and_b32_e32 v78, 7, v98
	v_ashrrev_i32_e32 v89, 3, v98
	s_cselect_b32 s10, s17, s18
	v_lshlrev_b32_e32 v106, 4, v78
	v_add_u32_e32 v94, s10, v89
	v_lshl_add_u32 v99, v78, 5, s14
	v_sub_u32_e32 v79, 7, v89
	v_add_u32_e32 v88, 0, v106
	v_subrev_u32_e32 v78, s16, v94
	v_cndmask_b32_e64 v79, v79, v89, s[8:9]
	v_mad_u64_u32 v[100:101], s[10:11], v78, s58, v[88:89]
	global_load_dwordx4 v[66:69], v[34:35], off
	global_load_dwordx4 v[54:57], v[34:35], off offset:64
	global_load_dwordx4 v[58:61], v[34:35], off offset:2048
	global_load_dwordx4 v[62:65], v[34:35], off offset:2112
	global_load_dwordx4 v[74:77], v[36:37], off
	global_load_dwordx4 v[70:73], v[36:37], off offset:64
	global_load_dwordx4 v[50:53], v[36:37], off offset:2048
	global_load_dwordx4 v[46:49], v[36:37], off offset:2112
	v_addc_co_u32_e32 v87, vcc, 0, v35, vcc
	global_load_dwordx4 v[34:37], v[42:43], off offset:64
	global_load_dwordx4 v[38:41], v[42:43], off offset:2048
	s_nop 0
	global_load_dwordx4 v[42:45], v[42:43], off offset:2112
	v_lshlrev_b32_e32 v158, 7, v79
	ds_read_b128 v[78:81], v100 offset:35200
	ds_read_b128 v[82:85], v100 offset:35840
	ds_read_b128 v[90:93], v100 offset:36480
	v_cmp_lt_i32_e64 s[10:11], 0, v94
	v_cmp_gt_i32_e32 vcc, s33, v94
	ds_read_b128 v[94:97], v99 offset:768
	s_waitcnt lgkmcnt(3)
	v_cndmask_b32_e64 v101, 0, v81, s[10:11]
	v_cndmask_b32_e64 v78, 0, v78, s[10:11]
	s_waitcnt lgkmcnt(1)
	v_cndmask_b32_e32 v81, 0, v90, vcc
	v_and_b32_e32 v90, 0xffff0000, v81
	v_and_b32_e32 v136, 0xffff0000, v78
	v_add_f32_e32 v90, v90, v136
	v_and_b32_e32 v140, 0xffff0000, v82
	v_fma_f32 v90, v90, 0.5, -v140
	ds_read_b128 v[136:139], v99 offset:784
	s_waitcnt lgkmcnt(1)
	v_fmac_f32_e32 v140, v95, v90
	v_add_f32_e32 v90, v140, v140
	v_lshlrev_b32_e32 v78, 16, v78
	v_lshlrev_b32_e32 v81, 16, v81
	v_mul_f32_e32 v90, 0x3fb8aa3b, v90
	v_add_f32_e32 v78, v81, v78
	v_lshlrev_b32_e32 v81, 16, v82
	v_exp_f32_e32 v90, v90
	v_fma_f32 v78, v78, 0.5, -v81
	v_fmac_f32_e32 v81, v94, v78
	v_add_f32_e32 v78, v81, v81
	v_cndmask_b32_e64 v79, 0, v79, s[10:11]
	v_mul_f32_e32 v78, 0x3fb8aa3b, v78
	v_cndmask_b32_e32 v82, 0, v91, vcc
	v_exp_f32_e32 v81, v78
	v_add_f32_e32 v78, 1.0, v90
	v_and_b32_e32 v90, 0xffff0000, v82
	v_and_b32_e32 v91, 0xffff0000, v79
	v_lshlrev_b32_e32 v79, 16, v79
	v_lshlrev_b32_e32 v82, 16, v82
	v_add_f32_e32 v79, v82, v79
	v_lshlrev_b32_e32 v82, 16, v83
	v_add_f32_e32 v90, v90, v91
	v_and_b32_e32 v91, 0xffff0000, v83
	v_fma_f32 v79, v79, 0.5, -v82
	v_fma_f32 v90, v90, 0.5, -v91
	v_fmac_f32_e32 v82, v96, v79
	v_fmac_f32_e32 v91, v97, v90
	v_add_f32_e32 v79, v82, v82
	v_add_f32_e32 v90, v91, v91
	v_mul_f32_e32 v79, 0x3fb8aa3b, v79
	v_mul_f32_e32 v90, 0x3fb8aa3b, v90
	v_exp_f32_e32 v83, v79
	v_exp_f32_e32 v90, v90
	v_add_f32_e32 v81, 1.0, v81
	v_rcp_f32_e32 v82, v81
	v_add_f32_e32 v81, 1.0, v83
	v_add_f32_e32 v79, 1.0, v90
	v_rcp_f32_e32 v83, v81
	v_rcp_f32_e32 v78, v78
	v_rcp_f32_e32 v79, v79
	v_cndmask_b32_e64 v90, 0, v80, s[10:11]
	v_pk_fma_f32 v[80:81], v[82:83], 2.0, 1.0 op_sel_hi:[1,0,0] neg_lo:[1,0,0] neg_hi:[1,0,0]
	v_cndmask_b32_e32 v91, 0, v92, vcc
	v_pk_fma_f32 v[78:79], v[78:79], 2.0, 1.0 op_sel_hi:[1,0,0] neg_lo:[1,0,0] neg_hi:[1,0,0]
	v_and_b32_sdwa v82, v81, v213 dst_sel:DWORD dst_unused:UNUSED_PAD src0_sel:WORD_1 src1_sel:DWORD
	v_and_b32_sdwa v83, v80, v213 dst_sel:DWORD dst_unused:UNUSED_PAD src0_sel:WORD_1 src1_sel:DWORD
	v_add3_u32 v92, v80, v83, s46
	v_add3_u32 v94, v81, v82, s46
	v_and_b32_sdwa v80, v79, v213 dst_sel:DWORD dst_unused:UNUSED_PAD src0_sel:WORD_1 src1_sel:DWORD
	v_and_b32_sdwa v81, v78, v213 dst_sel:DWORD dst_unused:UNUSED_PAD src0_sel:WORD_1 src1_sel:DWORD
	v_add3_u32 v79, v79, v80, s46
	v_add3_u32 v78, v78, v81, s46
	v_and_b32_e32 v80, 0xffff0000, v91
	v_and_b32_e32 v81, 0xffff0000, v90
	v_add_f32_e32 v80, v80, v81
	v_and_b32_e32 v81, 0xffff0000, v84
	v_fma_f32 v80, v80, 0.5, -v81
	s_waitcnt lgkmcnt(0)
	v_fmac_f32_e32 v81, v137, v80
	v_add_f32_e32 v80, v81, v81
	v_lshlrev_b32_e32 v81, 16, v90
	v_lshlrev_b32_e32 v82, 16, v91
	v_add_f32_e32 v81, v82, v81
	v_lshlrev_b32_e32 v82, 16, v84
	v_fma_f32 v81, v81, 0.5, -v82
	v_cndmask_b32_e32 v93, 0, v93, vcc
	v_fmac_f32_e32 v82, v136, v81
	v_add_f32_e32 v81, v82, v82
	v_and_b32_e32 v82, 0xffff0000, v93
	v_and_b32_e32 v83, 0xffff0000, v101
	v_add_f32_e32 v82, v82, v83
	v_and_b32_e32 v83, 0xffff0000, v85
	v_fma_f32 v82, v82, 0.5, -v83
	v_fmac_f32_e32 v83, v82, v139
	v_add_f32_e32 v82, v83, v83
	v_mul_f32_e32 v82, 0x3fb8aa3b, v82
	v_exp_f32_e32 v83, v82
	v_lshlrev_b32_e32 v82, 16, v101
	v_lshlrev_b32_e32 v84, 16, v93
	v_add_f32_e32 v82, v84, v82
	v_lshlrev_b32_e32 v84, 16, v85
	v_fma_f32 v82, v82, 0.5, -v84
	v_mul_f32_e32 v81, 0x3fb8aa3b, v81
	v_fmac_f32_e32 v84, v82, v138
	v_exp_f32_e32 v81, v81
	v_add_f32_e32 v82, v84, v84
	v_mul_f32_e32 v80, 0x3fb8aa3b, v80
	v_mul_f32_e32 v82, 0x3fb8aa3b, v82
	v_exp_f32_e32 v80, v80
	v_exp_f32_e32 v84, v82
	v_add_f32_e32 v81, 1.0, v81
	v_rcp_f32_e32 v82, v81
	v_add_f32_e32 v81, 1.0, v83
	v_add_f32_e32 v80, 1.0, v80
	v_rcp_f32_e32 v83, v81
	v_add_f32_e32 v81, 1.0, v84
	v_rcp_f32_e32 v80, v80
	v_rcp_f32_e32 v81, v81
	v_pk_fma_f32 v[82:83], v[82:83], 2.0, 1.0 op_sel_hi:[1,0,0] neg_lo:[1,0,0] neg_hi:[1,0,0]
	v_and_b32_e32 v79, 0xffff0000, v79
	v_and_b32_e32 v78, 0xffff0000, v78
	v_pk_fma_f32 v[80:81], v[80:81], 2.0, 1.0 op_sel_hi:[1,0,0] neg_lo:[1,0,0] neg_hi:[1,0,0]
	v_add3_u32 v159, s34, v158, v106
	v_and_b32_sdwa v84, v81, v213 dst_sel:DWORD dst_unused:UNUSED_PAD src0_sel:WORD_1 src1_sel:DWORD
	v_and_b32_sdwa v85, v80, v213 dst_sel:DWORD dst_unused:UNUSED_PAD src0_sel:WORD_1 src1_sel:DWORD
	v_add3_u32 v81, v81, v84, s46
	v_and_b32_sdwa v84, v83, v213 dst_sel:DWORD dst_unused:UNUSED_PAD src0_sel:WORD_1 src1_sel:DWORD
	v_add3_u32 v80, v80, v85, s46
	v_and_b32_sdwa v85, v82, v213 dst_sel:DWORD dst_unused:UNUSED_PAD src0_sel:WORD_1 src1_sel:DWORD
	v_add3_u32 v83, v83, v84, s46
	v_and_b32_e32 v80, 0xffff0000, v80
	v_add3_u32 v82, v82, v85, s46
	v_and_b32_e32 v83, 0xffff0000, v83
	v_or_b32_sdwa v79, v79, v94 dst_sel:DWORD dst_unused:UNUSED_PAD src0_sel:DWORD src1_sel:WORD_1
	v_or_b32_sdwa v78, v78, v92 dst_sel:DWORD dst_unused:UNUSED_PAD src0_sel:DWORD src1_sel:WORD_1
	v_or_b32_sdwa v81, v81, v83 dst_sel:DWORD dst_unused:UNUSED_PAD src0_sel:WORD_1 src1_sel:DWORD
	v_or_b32_sdwa v80, v80, v82 dst_sel:DWORD dst_unused:UNUSED_PAD src0_sel:DWORD src1_sel:WORD_1
	ds_write_b128 v159, v[78:81] offset:16384
	ds_read_b128 v[90:93], v100 offset:35328
	global_load_dwordx4 v[82:85], v[86:87], off offset:-4096
	global_load_dwordx4 v[78:81], v[86:87], off
	ds_read_b128 v[94:97], v100 offset:35968
	ds_read_b128 v[136:139], v100 offset:36608
	s_add_i32 s15, s15, s60
	s_sub_i32 s17, s71, s15
	s_waitcnt lgkmcnt(2)
	v_cndmask_b32_e64 v100, 0, v92, s[10:11]
	v_cndmask_b32_e64 v144, 0, v91, s[10:11]
	v_cndmask_b32_e64 v146, 0, v90, s[10:11]
	v_cndmask_b32_e64 v145, 0, v93, s[10:11]
	ds_read_b128 v[90:93], v99 offset:1024
	ds_read_b128 v[140:143], v99 offset:1040
	s_waitcnt lgkmcnt(2)
	v_cndmask_b32_e32 v155, 0, v137, vcc
	v_cndmask_b32_e32 v136, 0, v136, vcc
	v_and_b32_e32 v148, 0xffff0000, v146
	v_and_b32_e32 v150, 0xffff0000, v136
	v_and_b32_e32 v149, 0xffff0000, v144
	v_and_b32_e32 v151, 0xffff0000, v155
	v_pk_add_f32 v[148:149], v[148:149], v[150:151]
	v_and_b32_e32 v151, 0xffff0000, v95
	v_and_b32_e32 v150, 0xffff0000, v94
	v_pk_fma_f32 v[148:149], v[148:149], 0.5, v[150:151] op_sel_hi:[1,0,1] neg_lo:[0,0,1] neg_hi:[0,0,1]
	s_waitcnt lgkmcnt(1)
	v_mov_b32_e32 v156, v91
	v_mov_b32_e32 v157, v93
	v_pk_fma_f32 v[148:149], v[156:157], v[148:149], v[150:151]
	v_lshlrev_b32_e32 v152, 16, v146
	v_lshlrev_b32_e32 v154, 16, v136
	v_lshlrev_b32_e32 v153, 16, v144
	v_lshlrev_b32_e32 v155, 16, v155
	v_and_b32_sdwa v91, v149, v213 dst_sel:DWORD dst_unused:UNUSED_PAD src0_sel:WORD_1 src1_sel:DWORD
	v_and_b32_sdwa v93, v148, v213 dst_sel:DWORD dst_unused:UNUSED_PAD src0_sel:WORD_1 src1_sel:DWORD
	v_add3_u32 v91, v149, v91, s46
	v_add3_u32 v93, v148, v93, s46
	v_pk_add_f32 v[148:149], v[152:153], v[154:155]
	v_lshlrev_b32_e32 v95, 16, v95
	v_lshlrev_b32_e32 v94, 16, v94
	v_and_b32_e32 v136, 0xffff0000, v91
	v_pk_fma_f32 v[148:149], v[148:149], 0.5, v[94:95] op_sel_hi:[1,0,1] neg_lo:[0,0,1] neg_hi:[0,0,1]
	v_mov_b32_e32 v91, v92
	v_pk_fma_f32 v[90:91], v[90:91], v[148:149], v[94:95]
	v_cndmask_b32_e32 v160, 0, v138, vcc
	v_cndmask_b32_e32 v147, 0, v139, vcc
	v_and_b32_sdwa v94, v90, v213 dst_sel:DWORD dst_unused:UNUSED_PAD src0_sel:WORD_1 src1_sel:DWORD
	v_and_b32_e32 v101, 0xffff0000, v145
	v_and_b32_e32 v137, 0xffff0000, v147
	v_lshlrev_b32_e32 v145, 16, v145
	v_lshlrev_b32_e32 v147, 16, v147
	v_and_b32_e32 v93, 0xffff0000, v93
	v_and_b32_sdwa v92, v91, v213 dst_sel:DWORD dst_unused:UNUSED_PAD src0_sel:WORD_1 src1_sel:DWORD
	v_add3_u32 v90, v90, v94, s46
	v_and_b32_e32 v144, 0xffff0000, v100
	v_and_b32_e32 v146, 0xffff0000, v160
	v_add3_u32 v91, v91, v92, s46
	v_or_b32_sdwa v90, v93, v90 dst_sel:DWORD dst_unused:UNUSED_PAD src0_sel:DWORD src1_sel:WORD_1
	v_pk_add_f32 v[92:93], v[144:145], v[146:147]
	v_and_b32_e32 v94, 0xffff0000, v96
	v_lshlrev_b32_e32 v95, 16, v97
	s_waitcnt lgkmcnt(0)
	v_mov_b32_e32 v138, v141
	v_mov_b32_e32 v139, v142
	v_or_b32_sdwa v91, v136, v91 dst_sel:DWORD dst_unused:UNUSED_PAD src0_sel:DWORD src1_sel:WORD_1
	v_lshlrev_b32_e32 v100, 16, v100
	v_lshlrev_b32_e32 v136, 16, v160
	v_pk_fma_f32 v[92:93], v[92:93], 0.5, v[94:95] op_sel_hi:[1,0,1] neg_lo:[0,0,1] neg_hi:[0,0,1]
	v_lshlrev_b32_e32 v96, 16, v96
	v_pk_fma_f32 v[92:93], v[92:93], v[138:139], v[94:95]
	v_pk_add_f32 v[94:95], v[100:101], v[136:137]
	v_and_b32_e32 v97, 0xffff0000, v97
	v_pk_fma_f32 v[94:95], v[94:95], 0.5, v[96:97] op_sel_hi:[1,0,1] neg_lo:[0,0,1] neg_hi:[0,0,1]
	v_mov_b32_e32 v141, v143
	v_pk_fma_f32 v[94:95], v[94:95], v[140:141], v[96:97]
	v_and_b32_sdwa v96, v93, v213 dst_sel:DWORD dst_unused:UNUSED_PAD src0_sel:WORD_1 src1_sel:DWORD
	v_and_b32_sdwa v97, v92, v213 dst_sel:DWORD dst_unused:UNUSED_PAD src0_sel:WORD_1 src1_sel:DWORD
	v_add3_u32 v93, v93, v96, s46
	v_and_b32_sdwa v96, v95, v213 dst_sel:DWORD dst_unused:UNUSED_PAD src0_sel:WORD_1 src1_sel:DWORD
	s_and_b64 s[10:11], s[8:9], exec
	v_add3_u32 v92, v92, v97, s46
	v_and_b32_sdwa v97, v94, v213 dst_sel:DWORD dst_unused:UNUSED_PAD src0_sel:WORD_1 src1_sel:DWORD
	v_add3_u32 v95, v95, v96, s46
	s_cselect_b32 s10, s15, s17
	v_and_b32_e32 v92, 0xffff0000, v92
	v_add3_u32 v94, v94, v97, s46
	v_and_b32_e32 v95, 0xffff0000, v95
	v_add_u32_e32 v96, s10, v89
	v_or_b32_sdwa v93, v95, v93 dst_sel:DWORD dst_unused:UNUSED_PAD src0_sel:DWORD src1_sel:WORD_1
	v_or_b32_sdwa v92, v94, v92 dst_sel:DWORD dst_unused:UNUSED_PAD src0_sel:WORD_1 src1_sel:DWORD
	v_subrev_u32_e32 v89, s16, v96
	ds_write_b128 v159, v[90:93] offset:24576
	v_mad_u64_u32 v[100:101], s[10:11], v89, s58, v[88:89]
	ds_read_b128 v[88:91], v100 offset:35200
	ds_read_b128 v[92:95], v100 offset:35840
	ds_read_b128 v[136:139], v100 offset:36480
	v_cmp_lt_i32_e64 s[10:11], 0, v96
	v_cmp_gt_i32_e32 vcc, s33, v96
	ds_read_b128 v[140:143], v99 offset:768
	ds_read_b128 v[144:147], v99 offset:784
	s_waitcnt lgkmcnt(4)
	v_cndmask_b32_e64 v97, 0, v91, s[10:11]
	v_cndmask_b32_e64 v88, 0, v88, s[10:11]
	s_waitcnt lgkmcnt(2)
	v_cndmask_b32_e32 v91, 0, v136, vcc
	v_and_b32_e32 v101, 0xffff0000, v91
	v_and_b32_e32 v136, 0xffff0000, v88
	v_add_f32_e32 v101, v101, v136
	v_and_b32_e32 v136, 0xffff0000, v92
	v_fma_f32 v101, v101, 0.5, -v136
	s_waitcnt lgkmcnt(1)
	v_fmac_f32_e32 v136, v141, v101
	v_add_f32_e32 v101, v136, v136
	v_lshlrev_b32_e32 v88, 16, v88
	v_lshlrev_b32_e32 v91, 16, v91
	v_mul_f32_e32 v101, 0x3fb8aa3b, v101
	v_add_f32_e32 v88, v91, v88
	v_lshlrev_b32_e32 v91, 16, v92
	v_exp_f32_e32 v101, v101
	v_fma_f32 v88, v88, 0.5, -v91
	v_fmac_f32_e32 v91, v140, v88
	v_add_f32_e32 v88, v91, v91
	v_cndmask_b32_e64 v89, 0, v89, s[10:11]
	v_mul_f32_e32 v88, 0x3fb8aa3b, v88
	v_cndmask_b32_e32 v92, 0, v137, vcc
	v_exp_f32_e32 v91, v88
	v_add_f32_e32 v88, 1.0, v101
	v_and_b32_e32 v101, 0xffff0000, v92
	v_and_b32_e32 v136, 0xffff0000, v89
	v_lshlrev_b32_e32 v89, 16, v89
	v_lshlrev_b32_e32 v92, 16, v92
	v_add_f32_e32 v89, v92, v89
	v_lshlrev_b32_e32 v92, 16, v93
	v_add_f32_e32 v101, v101, v136
	v_and_b32_e32 v136, 0xffff0000, v93
	v_fma_f32 v89, v89, 0.5, -v92
	v_fma_f32 v101, v101, 0.5, -v136
	v_fmac_f32_e32 v92, v142, v89
	v_fmac_f32_e32 v136, v143, v101
	v_add_f32_e32 v89, v92, v92
	v_add_f32_e32 v101, v136, v136
	v_mul_f32_e32 v89, 0x3fb8aa3b, v89
	v_mul_f32_e32 v101, 0x3fb8aa3b, v101
	v_exp_f32_e32 v93, v89
	v_exp_f32_e32 v101, v101
	v_add_f32_e32 v91, 1.0, v91
	v_rcp_f32_e32 v92, v91
	v_add_f32_e32 v91, 1.0, v93
	v_add_f32_e32 v89, 1.0, v101
	v_rcp_f32_e32 v93, v91
	v_rcp_f32_e32 v88, v88
	v_rcp_f32_e32 v89, v89
	v_cndmask_b32_e64 v101, 0, v90, s[10:11]
	v_pk_fma_f32 v[90:91], v[92:93], 2.0, 1.0 op_sel_hi:[1,0,0] neg_lo:[1,0,0] neg_hi:[1,0,0]
	v_cndmask_b32_e32 v136, 0, v138, vcc
	v_pk_fma_f32 v[88:89], v[88:89], 2.0, 1.0 op_sel_hi:[1,0,0] neg_lo:[1,0,0] neg_hi:[1,0,0]
	v_and_b32_sdwa v92, v91, v213 dst_sel:DWORD dst_unused:UNUSED_PAD src0_sel:WORD_1 src1_sel:DWORD
	v_and_b32_sdwa v93, v90, v213 dst_sel:DWORD dst_unused:UNUSED_PAD src0_sel:WORD_1 src1_sel:DWORD
	v_add3_u32 v137, v90, v93, s46
	v_add3_u32 v138, v91, v92, s46
	v_and_b32_sdwa v90, v89, v213 dst_sel:DWORD dst_unused:UNUSED_PAD src0_sel:WORD_1 src1_sel:DWORD
	v_and_b32_sdwa v91, v88, v213 dst_sel:DWORD dst_unused:UNUSED_PAD src0_sel:WORD_1 src1_sel:DWORD
	v_add3_u32 v89, v89, v90, s46
	v_add3_u32 v88, v88, v91, s46
	v_and_b32_e32 v90, 0xffff0000, v136
	v_and_b32_e32 v91, 0xffff0000, v101
	v_add_f32_e32 v90, v90, v91
	v_and_b32_e32 v91, 0xffff0000, v94
	v_fma_f32 v90, v90, 0.5, -v91
	s_waitcnt lgkmcnt(0)
	v_fmac_f32_e32 v91, v145, v90
	v_add_f32_e32 v90, v91, v91
	v_lshlrev_b32_e32 v91, 16, v101
	v_lshlrev_b32_e32 v92, 16, v136
	v_add_f32_e32 v91, v92, v91
	v_lshlrev_b32_e32 v92, 16, v94
	v_fma_f32 v91, v91, 0.5, -v92
	v_cndmask_b32_e32 v96, 0, v139, vcc
	v_fmac_f32_e32 v92, v144, v91
	v_add_f32_e32 v91, v92, v92
	v_and_b32_e32 v92, 0xffff0000, v96
	v_and_b32_e32 v93, 0xffff0000, v97
	v_add_f32_e32 v92, v92, v93
	v_and_b32_e32 v93, 0xffff0000, v95
	v_fma_f32 v92, v92, 0.5, -v93
	v_fmac_f32_e32 v93, v92, v147
	v_add_f32_e32 v92, v93, v93
	v_mul_f32_e32 v92, 0x3fb8aa3b, v92
	v_exp_f32_e32 v93, v92
	v_lshlrev_b32_e32 v92, 16, v97
	v_lshlrev_b32_e32 v94, 16, v96
	v_add_f32_e32 v92, v94, v92
	v_lshlrev_b32_e32 v94, 16, v95
	v_fma_f32 v92, v92, 0.5, -v94
	v_mul_f32_e32 v91, 0x3fb8aa3b, v91
	v_fmac_f32_e32 v94, v92, v146
	v_exp_f32_e32 v91, v91
	v_add_f32_e32 v92, v94, v94
	v_mul_f32_e32 v90, 0x3fb8aa3b, v90
	v_mul_f32_e32 v92, 0x3fb8aa3b, v92
	v_exp_f32_e32 v90, v90
	v_exp_f32_e32 v94, v92
	v_add_f32_e32 v91, 1.0, v91
	v_rcp_f32_e32 v92, v91
	v_add_f32_e32 v91, 1.0, v93
	v_add_f32_e32 v90, 1.0, v90
	v_rcp_f32_e32 v93, v91
	v_add_f32_e32 v91, 1.0, v94
	v_rcp_f32_e32 v90, v90
	v_rcp_f32_e32 v91, v91
	v_pk_fma_f32 v[92:93], v[92:93], 2.0, 1.0 op_sel_hi:[1,0,0] neg_lo:[1,0,0] neg_hi:[1,0,0]
	v_and_b32_e32 v89, 0xffff0000, v89
	v_and_b32_e32 v88, 0xffff0000, v88
	v_pk_fma_f32 v[90:91], v[90:91], 2.0, 1.0 op_sel_hi:[1,0,0] neg_lo:[1,0,0] neg_hi:[1,0,0]
	v_add3_u32 v106, s61, v158, v106
	v_and_b32_sdwa v94, v91, v213 dst_sel:DWORD dst_unused:UNUSED_PAD src0_sel:WORD_1 src1_sel:DWORD
	v_and_b32_sdwa v95, v90, v213 dst_sel:DWORD dst_unused:UNUSED_PAD src0_sel:WORD_1 src1_sel:DWORD
	v_add3_u32 v91, v91, v94, s46
	v_and_b32_sdwa v94, v93, v213 dst_sel:DWORD dst_unused:UNUSED_PAD src0_sel:WORD_1 src1_sel:DWORD
	v_add3_u32 v90, v90, v95, s46
	v_and_b32_sdwa v95, v92, v213 dst_sel:DWORD dst_unused:UNUSED_PAD src0_sel:WORD_1 src1_sel:DWORD
	v_add3_u32 v93, v93, v94, s46
	v_and_b32_e32 v90, 0xffff0000, v90
	v_add3_u32 v92, v92, v95, s46
	v_and_b32_e32 v93, 0xffff0000, v93
	v_or_b32_sdwa v89, v89, v138 dst_sel:DWORD dst_unused:UNUSED_PAD src0_sel:DWORD src1_sel:WORD_1
	v_or_b32_sdwa v88, v88, v137 dst_sel:DWORD dst_unused:UNUSED_PAD src0_sel:DWORD src1_sel:WORD_1
	v_or_b32_sdwa v91, v91, v93 dst_sel:DWORD dst_unused:UNUSED_PAD src0_sel:WORD_1 src1_sel:DWORD
	v_or_b32_sdwa v90, v90, v92 dst_sel:DWORD dst_unused:UNUSED_PAD src0_sel:DWORD src1_sel:WORD_1
	ds_write_b128 v106, v[88:91] offset:16384
	ds_read_b128 v[136:139], v100 offset:35328
	global_load_dwordx4 v[94:97], v[86:87], off offset:64
	global_load_dwordx4 v[90:93], v[86:87], off offset:2048
	s_nop 0
	global_load_dwordx4 v[86:89], v[86:87], off offset:2112
	ds_read_b128 v[140:143], v100 offset:35968
	ds_read_b128 v[144:147], v100 offset:36608
	s_waitcnt lgkmcnt(2)
	v_cndmask_b32_e64 v100, 0, v138, s[10:11]
	v_cndmask_b32_e64 v152, 0, v137, s[10:11]
	v_cndmask_b32_e64 v154, 0, v136, s[10:11]
	v_cndmask_b32_e64 v153, 0, v139, s[10:11]
	ds_read_b128 v[136:139], v99 offset:1024
	ds_read_b128 v[148:151], v99 offset:1040
	s_waitcnt lgkmcnt(2)
	v_cndmask_b32_e32 v163, 0, v145, vcc
	v_cndmask_b32_e32 v99, 0, v144, vcc
	v_and_b32_e32 v156, 0xffff0000, v154
	v_and_b32_e32 v158, 0xffff0000, v99
	v_and_b32_e32 v157, 0xffff0000, v152
	v_and_b32_e32 v159, 0xffff0000, v163
	v_pk_add_f32 v[156:157], v[156:157], v[158:159]
	v_and_b32_e32 v159, 0xffff0000, v141
	v_and_b32_e32 v158, 0xffff0000, v140
	v_pk_fma_f32 v[156:157], v[156:157], 0.5, v[158:159] op_sel_hi:[1,0,1] neg_lo:[0,0,1] neg_hi:[0,0,1]
	s_waitcnt lgkmcnt(1)
	v_mov_b32_e32 v164, v137
	v_mov_b32_e32 v165, v139
	v_pk_fma_f32 v[156:157], v[164:165], v[156:157], v[158:159]
	v_lshlrev_b32_e32 v160, 16, v154
	v_lshlrev_b32_e32 v162, 16, v99
	v_lshlrev_b32_e32 v161, 16, v152
	v_lshlrev_b32_e32 v163, 16, v163
	v_and_b32_sdwa v99, v157, v213 dst_sel:DWORD dst_unused:UNUSED_PAD src0_sel:WORD_1 src1_sel:DWORD
	v_and_b32_sdwa v137, v156, v213 dst_sel:DWORD dst_unused:UNUSED_PAD src0_sel:WORD_1 src1_sel:DWORD
	v_add3_u32 v99, v157, v99, s46
	v_add3_u32 v137, v156, v137, s46
	v_pk_add_f32 v[156:157], v[160:161], v[162:163]
	v_lshlrev_b32_e32 v141, 16, v141
	v_lshlrev_b32_e32 v140, 16, v140
	v_and_b32_e32 v139, 0xffff0000, v137
	v_pk_fma_f32 v[156:157], v[156:157], 0.5, v[140:141] op_sel_hi:[1,0,1] neg_lo:[0,0,1] neg_hi:[0,0,1]
	v_mov_b32_e32 v137, v138
	v_pk_fma_f32 v[136:137], v[136:137], v[156:157], v[140:141]
	v_cndmask_b32_e32 v168, 0, v146, vcc
	v_cndmask_b32_e32 v144, 0, v147, vcc
	v_and_b32_sdwa v140, v136, v213 dst_sel:DWORD dst_unused:UNUSED_PAD src0_sel:WORD_1 src1_sel:DWORD
	v_and_b32_e32 v101, 0xffff0000, v153
	v_lshlrev_b32_e32 v153, 16, v153
	v_lshlrev_b32_e32 v155, 16, v144
	v_and_b32_sdwa v138, v137, v213 dst_sel:DWORD dst_unused:UNUSED_PAD src0_sel:WORD_1 src1_sel:DWORD
	v_add3_u32 v136, v136, v140, s46
	v_and_b32_e32 v152, 0xffff0000, v100
	v_and_b32_e32 v154, 0xffff0000, v168
	v_add3_u32 v137, v137, v138, s46
	v_or_b32_sdwa v136, v139, v136 dst_sel:DWORD dst_unused:UNUSED_PAD src0_sel:DWORD src1_sel:WORD_1
	v_pk_add_f32 v[138:139], v[152:153], v[154:155]
	v_and_b32_e32 v140, 0xffff0000, v142
	v_lshlrev_b32_e32 v141, 16, v143
	v_and_b32_e32 v145, 0xffff0000, v144
	s_waitcnt lgkmcnt(0)
	v_mov_b32_e32 v146, v149
	v_mov_b32_e32 v147, v150
	v_lshlrev_b32_e32 v100, 16, v100
	v_lshlrev_b32_e32 v144, 16, v168
	v_pk_fma_f32 v[138:139], v[138:139], 0.5, v[140:141] op_sel_hi:[1,0,1] neg_lo:[0,0,1] neg_hi:[0,0,1]
	v_pk_add_f32 v[100:101], v[100:101], v[144:145]
	v_pk_fma_f32 v[138:139], v[138:139], v[146:147], v[140:141]
	v_lshlrev_b32_e32 v140, 16, v142
	v_and_b32_e32 v141, 0xffff0000, v143
	v_and_b32_e32 v99, 0xffff0000, v99
	v_pk_fma_f32 v[100:101], v[100:101], 0.5, v[140:141] op_sel_hi:[1,0,1] neg_lo:[0,0,1] neg_hi:[0,0,1]
	v_mov_b32_e32 v149, v151
	v_or_b32_sdwa v137, v99, v137 dst_sel:DWORD dst_unused:UNUSED_PAD src0_sel:DWORD src1_sel:WORD_1
	v_pk_fma_f32 v[100:101], v[100:101], v[148:149], v[140:141]
	v_and_b32_sdwa v99, v139, v213 dst_sel:DWORD dst_unused:UNUSED_PAD src0_sel:WORD_1 src1_sel:DWORD
	v_add3_u32 v99, v139, v99, s46
	v_and_b32_sdwa v139, v101, v213 dst_sel:DWORD dst_unused:UNUSED_PAD src0_sel:WORD_1 src1_sel:DWORD
	v_and_b32_sdwa v140, v138, v213 dst_sel:DWORD dst_unused:UNUSED_PAD src0_sel:WORD_1 src1_sel:DWORD
	v_add3_u32 v101, v101, v139, s46
	v_add3_u32 v138, v138, v140, s46
	v_and_b32_sdwa v140, v100, v213 dst_sel:DWORD dst_unused:UNUSED_PAD src0_sel:WORD_1 src1_sel:DWORD
	v_and_b32_e32 v101, 0xffff0000, v101
	v_and_b32_e32 v138, 0xffff0000, v138
	v_add3_u32 v100, v100, v140, s46
	v_or_b32_sdwa v139, v101, v99 dst_sel:DWORD dst_unused:UNUSED_PAD src0_sel:DWORD src1_sel:WORD_1
	v_and_b32_e32 v99, 15, v98
	v_or_b32_sdwa v138, v100, v138 dst_sel:DWORD dst_unused:UNUSED_PAD src0_sel:WORD_1 src1_sel:DWORD
	v_or_b32_e32 v100, s0, v99
	ds_write_b128 v106, v[136:139] offset:24576
	v_and_b32_e32 v101, -16, v98
	v_lshlrev_b32_e32 v100, 7, v100
	s_waitcnt lgkmcnt(0)
	v_add3_u32 v100, 0, v100, v101
	ds_read_b128 v[136:139], v100 offset:16384
	ds_read_b128 v[140:143], v100 offset:16448
	s_waitcnt vmcnt(15) lgkmcnt(1)
	v_mfma_f32_16x16x32_bf16 v[66:69], v[136:139], v[66:69], 0
	s_waitcnt lgkmcnt(0)
	s_waitcnt vmcnt(14) lgkmcnt(0)
	v_mfma_f32_16x16x32_bf16 v[54:57], v[140:143], v[54:57], v[66:69]
	s_nop 5
	v_lshl_add_u32 v66, v99, 2, s14
	v_add_u32_e32 v68, 0x400, v66
	ds_read2_b32 v[66:67], v68 offset0:64 offset1:80
	s_waitcnt vmcnt(9)
	v_mfma_f32_16x16x32_bf16 v[50:53], v[136:139], v[50:53], 0
	v_lshrrev_b32_e32 v69, 2, v98
	v_and_b32_e32 v69, 0x1fffffc, v69
	v_add_lshl_u32 v69, v69, s0, 7
	s_waitcnt lgkmcnt(0)
	v_add_f32_e32 v54, v54, v66
	v_mul_f32_e32 v54, 0xbfb8aa3b, v54
	s_waitcnt vmcnt(8)
	v_mfma_f32_16x16x32_bf16 v[46:49], v[140:143], v[46:49], v[50:53]
	v_exp_f32_e32 v54, v54
	s_nop 1
	v_add_f32_e32 v51, v55, v66
	v_mul_f32_e32 v51, 0xbfb8aa3b, v51
	v_add_f32_e32 v52, v56, v66
	v_exp_f32_e32 v51, v51
	v_mul_f32_e32 v52, 0xbfb8aa3b, v52
	v_exp_f32_e32 v52, v52
	v_mfma_f32_16x16x32_bf16 v[58:61], v[136:139], v[58:61], 0
	v_lshlrev_b32_e32 v50, 1, v99
	v_add3_u32 v69, 0, v69, v50
	v_add_f32_e32 v50, 1.0, v54
	v_rcp_f32_e32 v50, v50
	v_add_f32_e32 v51, 1.0, v51
	v_rcp_f32_e32 v51, v51
	v_add_f32_e32 v52, 1.0, v52
	v_mfma_f32_16x16x32_bf16 v[58:61], v[140:143], v[62:65], v[58:61]
	v_rcp_f32_e32 v52, v52
	v_fma_mixlo_f16 v50, v50, s47, 0
	ds_write_b16 v69, v50 offset:16384
	v_fma_mixlo_f16 v50, v51, s47, 0
	ds_write_b16 v69, v50 offset:16512
	v_fma_mixlo_f16 v50, v52, s47, 0
	v_add_f32_e32 v51, v57, v66
	s_nop 0
	v_add_f32_e32 v52, v58, v67
	v_mul_f32_e32 v51, 0xbfb8aa3b, v51
	v_mul_f32_e32 v52, 0xbfb8aa3b, v52
	v_exp_f32_e32 v51, v51
	v_exp_f32_e32 v52, v52
	ds_write_b16 v69, v50 offset:16640
	v_mfma_f32_16x16x32_bf16 v[62:65], v[136:139], v[74:77], 0
	v_add_f32_e32 v50, 1.0, v51
	v_add_f32_e32 v51, 1.0, v52
	v_add_f32_e32 v52, v59, v67
	v_rcp_f32_e32 v50, v50
	v_mul_f32_e32 v52, 0xbfb8aa3b, v52
	v_rcp_f32_e32 v51, v51
	v_exp_f32_e32 v52, v52
	v_fma_mixlo_f16 v50, v50, s47, 0
	ds_write_b16 v69, v50 offset:16768
	v_fma_mixlo_f16 v50, v51, s47, 0
	v_add_f32_e32 v51, 1.0, v52
	v_add_f32_e32 v52, v60, v67
	v_rcp_f32_e32 v51, v51
	v_mul_f32_e32 v52, 0xbfb8aa3b, v52
	v_exp_f32_e32 v52, v52
	ds_write_b16 v69, v50 offset:16416
	v_fma_mixlo_f16 v50, v51, s47, 0
	ds_write_b16 v69, v50 offset:16544
	v_add_f32_e32 v50, 1.0, v52
	v_rcp_f32_e32 v52, v50
	v_add_f32_e32 v50, v61, v67
	v_mul_f32_e32 v50, 0xbfb8aa3b, v50
	v_exp_f32_e32 v53, v50
	ds_read2_b32 v[50:51], v68 offset0:96 offset1:112
	v_mfma_f32_16x16x32_bf16 v[62:65], v[140:143], v[70:73], v[62:65]
	v_fma_mixlo_f16 v52, v52, s47, 0
	ds_write_b16 v69, v52 offset:16672
	v_add_f32_e32 v52, 1.0, v53
	s_waitcnt lgkmcnt(1)
	v_add_f32_e32 v46, v46, v51
	v_mul_f32_e32 v46, 0xbfb8aa3b, v46
	s_nop 1
	v_add_f32_e32 v53, v62, v50
	v_exp_f32_e32 v46, v46
	v_mul_f32_e32 v53, 0xbfb8aa3b, v53
	v_exp_f32_e32 v53, v53
	v_add_f32_e32 v47, v47, v51
	v_add_f32_e32 v46, 1.0, v46
	v_add_f32_e32 v54, v63, v50
	v_rcp_f32_e32 v46, v46
	v_mul_f32_e32 v47, 0xbfb8aa3b, v47
	v_rcp_f32_e32 v52, v52
	v_mul_f32_e32 v54, 0xbfb8aa3b, v54
	v_add_f32_e32 v53, 1.0, v53
	v_exp_f32_e32 v47, v47
	v_exp_f32_e32 v54, v54
	v_rcp_f32_e32 v53, v53
	v_fma_mixlo_f16 v46, v46, s47, 0
	v_fma_mixlo_f16 v52, v52, s47, 0
	ds_write_b16 v69, v46 offset:16480
	v_add_f32_e32 v46, 1.0, v47
	v_add_f32_e32 v47, v48, v51
	v_add_f32_e32 v54, 1.0, v54
	ds_write_b16 v69, v52 offset:16800
	v_fma_mixlo_f16 v52, v53, s47, 0
	v_add_f32_e32 v53, v64, v50
	v_add_f32_e32 v50, v65, v50
	v_mul_f32_e32 v47, 0xbfb8aa3b, v47
	v_add_f32_e32 v48, v49, v51
	v_rcp_f32_e32 v54, v54
	v_mul_f32_e32 v53, 0xbfb8aa3b, v53
	v_mul_f32_e32 v50, 0xbfb8aa3b, v50
	v_exp_f32_e32 v47, v47
	v_mul_f32_e32 v48, 0xbfb8aa3b, v48
	v_exp_f32_e32 v53, v53
	v_exp_f32_e32 v50, v50
	v_exp_f32_e32 v48, v48
	ds_write_b16 v69, v52 offset:16448
	v_fma_mixlo_f16 v52, v54, s47, 0
	v_rcp_f32_e32 v46, v46
	v_add_f32_e32 v47, 1.0, v47
	ds_write_b16 v69, v52 offset:16576
	v_add_f32_e32 v52, 1.0, v53
	v_add_f32_e32 v50, 1.0, v50
	v_rcp_f32_e32 v47, v47
	v_add_f32_e32 v48, 1.0, v48
	v_rcp_f32_e32 v52, v52
	v_rcp_f32_e32 v50, v50
	v_rcp_f32_e32 v48, v48
	v_fma_mixlo_f16 v46, v46, s47, 0
	ds_write_b16 v69, v46 offset:16608
	v_fma_mixlo_f16 v46, v47, s47, 0
	v_fma_mixlo_f16 v52, v52, s47, 0
	v_fma_mixlo_f16 v50, v50, s47, 0
	ds_write_b16 v69, v46 offset:16736
	v_fma_mixlo_f16 v46, v48, s47, 0
	ds_write_b16 v69, v52 offset:16704
	ds_write_b16 v69, v50 offset:16832
	ds_write_b16 v69, v46 offset:16864
	ds_read_b128 v[46:49], v100 offset:24576
	ds_read_b128 v[50:53], v100 offset:24640
	s_waitcnt vmcnt(4) lgkmcnt(1)
	v_mfma_f32_16x16x32_bf16 v[54:57], v[46:49], v[82:85], 0
	s_waitcnt lgkmcnt(0)
	s_waitcnt lgkmcnt(0)
	v_mfma_f32_16x16x32_bf16 v[34:37], v[50:53], v[34:37], v[54:57]
	s_nop 5
	ds_read2_b32 v[54:55], v68 offset0:128 offset1:144
	v_mfma_f32_16x16x32_bf16 v[38:41], v[46:49], v[38:41], 0
	s_waitcnt lgkmcnt(0)
	v_add_f32_e32 v34, v34, v54
	v_mul_f32_e32 v34, 0xbfb8aa3b, v34
	v_exp_f32_e32 v34, v34
	v_add_f32_e32 v35, v35, v54
	v_mul_f32_e32 v35, 0xbfb8aa3b, v35
	v_exp_f32_e32 v35, v35
	v_add_f32_e32 v34, 1.0, v34
	v_rcp_f32_e32 v34, v34
	v_mfma_f32_16x16x32_bf16 v[38:41], v[50:53], v[42:45], v[38:41]
	v_cvt_f16_f32_e32 v34, v34
	s_waitcnt vmcnt(3)
	v_mfma_f32_16x16x32_bf16 v[42:45], v[46:49], v[78:81], 0
	ds_write_b16 v69, v34 offset:24576
	v_add_f32_e32 v34, 1.0, v35
	v_add_f32_e32 v35, v36, v54
	v_add_f32_e32 v36, v37, v54
	v_mul_f32_e32 v35, 0xbfb8aa3b, v35
	v_mul_f32_e32 v36, 0xbfb8aa3b, v36
	v_exp_f32_e32 v35, v35
	v_exp_f32_e32 v36, v36
	v_rcp_f32_e32 v34, v34
	v_add_f32_e32 v37, v38, v55
	v_add_f32_e32 v35, 1.0, v35
	v_add_f32_e32 v36, 1.0, v36
	v_mul_f32_e32 v37, 0xbfb8aa3b, v37
	v_cvt_f16_f32_e32 v34, v34
	v_rcp_f32_e32 v35, v35
	v_rcp_f32_e32 v36, v36
	v_exp_f32_e32 v37, v37
	ds_write_b16 v69, v34 offset:24704
	v_cvt_f16_f32_e32 v34, v35
	v_cvt_f16_f32_e32 v35, v36
	v_add_f32_e32 v36, 1.0, v37
	v_add_f32_e32 v37, v39, v55
	v_mul_f32_e32 v37, 0xbfb8aa3b, v37
	v_exp_f32_e32 v37, v37
	ds_write_b16 v69, v34 offset:24832
	ds_write_b16 v69, v35 offset:24960
	v_add_f32_e32 v35, v40, v55
	v_mul_f32_e32 v35, 0xbfb8aa3b, v35
	v_add_f32_e32 v34, 1.0, v37
	v_add_f32_e32 v37, v41, v55
	v_rcp_f32_e32 v36, v36
	v_exp_f32_e32 v35, v35
	v_mul_f32_e32 v37, 0xbfb8aa3b, v37
	v_exp_f32_e32 v37, v37
	v_cvt_f16_f32_e32 v36, v36
	v_rcp_f32_e32 v38, v34
	v_add_f32_e32 v34, 1.0, v35
	v_rcp_f32_e32 v39, v34
	v_add_f32_e32 v34, 1.0, v37
	v_rcp_f32_e32 v37, v34
	ds_read2_b32 v[34:35], v68 offset0:160 offset1:176
	s_waitcnt vmcnt(2)
	v_mfma_f32_16x16x32_bf16 v[42:45], v[50:53], v[94:97], v[42:45]
	ds_write_b16 v69, v36 offset:24608
	v_cvt_f16_f32_e32 v36, v38
	v_cvt_f16_f32_e32 v38, v39
	v_cvt_f16_f32_e32 v37, v37
	ds_write_b16 v69, v36 offset:24736
	ds_write_b16 v69, v38 offset:24864
	ds_write_b16 v69, v37 offset:24992
	s_waitcnt lgkmcnt(4)
	v_add_f32_e32 v39, v42, v34
	v_mul_f32_e32 v39, 0xbfb8aa3b, v39
	v_add_f32_e32 v37, v43, v34
	v_exp_f32_e32 v39, v39
	v_mul_f32_e32 v37, 0xbfb8aa3b, v37
	v_add_f32_e32 v38, v44, v34
	v_exp_f32_e32 v37, v37
	v_mul_f32_e32 v38, 0xbfb8aa3b, v38
	v_exp_f32_e32 v38, v38
	v_add_f32_e32 v36, 1.0, v39
	v_add_f32_e32 v34, v45, v34
	s_waitcnt vmcnt(1)
	v_mfma_f32_16x16x32_bf16 v[46:49], v[46:49], v[90:93], 0
	v_rcp_f32_e32 v36, v36
	v_add_f32_e32 v37, 1.0, v37
	v_mul_f32_e32 v34, 0xbfb8aa3b, v34
	v_rcp_f32_e32 v37, v37
	v_add_f32_e32 v38, 1.0, v38
	v_exp_f32_e32 v34, v34
	v_rcp_f32_e32 v38, v38
	s_waitcnt vmcnt(0)
	v_mfma_f32_16x16x32_bf16 v[46:49], v[50:53], v[86:89], v[46:49]
	v_cvt_f16_f32_e32 v36, v36
	v_cvt_f16_f32_e32 v37, v37
	v_add_f32_e32 v34, 1.0, v34
	v_cvt_f16_f32_e32 v38, v38
	v_rcp_f32_e32 v34, v34
	ds_write_b16 v69, v36 offset:24640
	ds_write_b16 v69, v37 offset:24768
	ds_write_b16 v69, v38 offset:24896
	v_add_f32_e32 v36, v46, v35
	v_add_f32_e32 v37, v47, v35
	v_mul_f32_e32 v36, 0xbfb8aa3b, v36
	v_mul_f32_e32 v37, 0xbfb8aa3b, v37
	v_cvt_f16_f32_e32 v34, v34
	v_exp_f32_e32 v36, v36
	v_exp_f32_e32 v37, v37
	ds_write_b16 v69, v34 offset:25024
	v_add_f32_e32 v34, 1.0, v36
	v_add_f32_e32 v36, 1.0, v37
	v_add_f32_e32 v37, v48, v35
	v_mul_f32_e32 v37, 0xbfb8aa3b, v37
	v_add_f32_e32 v35, v49, v35
	v_exp_f32_e32 v37, v37
	v_mul_f32_e32 v35, 0xbfb8aa3b, v35
	v_exp_f32_e32 v35, v35
	v_rcp_f32_e32 v34, v34
	v_rcp_f32_e32 v36, v36
	v_add_f32_e32 v37, 1.0, v37
	v_rcp_f32_e32 v37, v37
	v_add_f32_e32 v35, 1.0, v35
	v_rcp_f32_e32 v35, v35
	v_cvt_f16_f32_e32 v34, v34
	v_cvt_f16_f32_e32 v36, v36
	v_cvt_f16_f32_e32 v37, v37
	v_cvt_f16_f32_e32 v35, v35
	ds_write_b16 v69, v34 offset:24672
	ds_write_b16 v69, v36 offset:24800
	ds_write_b16 v69, v37 offset:24928
	ds_write_b16 v69, v35 offset:25056
	s_setprio 0
